# PLE gate epilogue software-pipelined: each row group's residual/pp/ssq loads fly under the previous group's processing (was: all four groups loaded serially, then processed)
# baseline (speedup 1.0000x reference)
.LBB0_948:
	s_lshl_b32 s10, s20, 8
	s_add_i32 s10, s10, s61
	v_mbcnt_lo_u32_b32 v124, -1, 0
	v_mbcnt_hi_u32_b32 v124, -1, v124
	s_nop 0
	v_ashrrev_i32_e32 v122, 1, v124
	v_and_or_b32 v208, v124, 15, s10
	s_lshl_b32 s10, s82, 8
	v_and_b32_e32 v122, -8, v122
	s_or_b32 s10, s10, s68
	v_add_u32_e32 v204, s10, v122
	v_ashrrev_i32_e32 v122, 2, v124
	v_and_b32_e32 v122, -4, v122
	v_ashrrev_i32_e32 v123, 31, v122
	v_ashrrev_i32_e32 v209, 31, v208
	v_ashrrev_i32_e32 v205, 31, v204
	v_lshl_add_u64 v[206:207], v[122:123], 2, s[6:7]
	v_lshlrev_b64 v[122:123], 10, v[208:209]
	v_lshl_add_u64 v[122:123], v[122:123], 0, v[204:205]
	v_lshlrev_b32_e32 v125, 2, v124
	v_lshlrev_b64 v[122:123], 1, v[122:123]
	v_xor_b32_e32 v229, 64, v125
	v_xor_b32_e32 v228, 0x80, v125
	v_cmp_gt_u32_e32 vcc, 16, v124
	v_lshl_add_u64 v[124:125], s[88:89], 0, v[122:123]
	v_lshl_add_u64 v[122:123], s[62:63], 0, v[122:123]
	v_lshlrev_b64 v[226:227], 6, v[208:209]
	v_or_b32_e32 v224, 16, v208
	v_ashrrev_i32_e32 v225, 31, v224
	v_lshlrev_b64 v[222:223], 6, v[224:225]
	v_or_b32_e32 v218, 32, v208
	v_ashrrev_i32_e32 v219, 31, v218
	v_lshlrev_b64 v[220:221], 6, v[218:219]
	v_or_b32_e32 v214, 48, v208
	v_ashrrev_i32_e32 v215, 31, v214
	v_lshlrev_b64 v[216:217], 6, v[214:215]
	v_lshl_add_u64 v[210:211], v[206:207], 0, v[216:217]
	global_load_dwordx4 v[242:245], v[210:211], off
	global_load_dwordx4 v[190:193], v[124:125], off
	global_load_dwordx4 v[186:189], v[122:123], off
	global_load_dwordx4 v[182:185], v[124:125], off offset:256
	global_load_dwordx4 v[178:181], v[122:123], off offset:256
	v_lshl_add_u64 v[122:123], v[206:207], 0, v[226:227]
	global_load_dwordx4 v[122:125], v[122:123], off
	s_waitcnt vmcnt(0)
	v_lshlrev_b32_e32 v238, 16, v190
	v_and_b32_e32 v239, 0xffff0000, v190
	v_lshlrev_b32_e32 v190, 16, v191
	v_and_b32_e32 v191, 0xffff0000, v191
	v_mov_b32_e32 v126, v123
	v_mov_b32_e32 v127, v124
	v_mov_b32_e32 v123, v125
	v_pk_add_f32 v[122:123], v[126:127], v[122:123]
	s_nop 0
	v_add_f32_e32 v122, v122, v123
	ds_bpermute_b32 v123, v229, v122
	s_waitcnt lgkmcnt(0)
	v_add_f32_e32 v122, v122, v123
	ds_bpermute_b32 v123, v228, v122
	s_waitcnt lgkmcnt(0)
	v_add_f32_e32 v122, v122, v123
	v_fmamk_f32 v122, v122, 0x3a800000, v240
	v_rsq_f32_e32 v236, v122
	v_lshlrev_b64 v[122:123], 10, v[224:225]
	v_lshl_add_u64 v[122:123], v[122:123], 0, v[204:205]
	v_lshlrev_b64 v[122:123], 1, v[122:123]
	v_lshl_add_u64 v[124:125], s[88:89], 0, v[122:123]
	v_lshl_add_u64 v[122:123], s[62:63], 0, v[122:123]
	global_load_dwordx4 v[174:177], v[124:125], off
	global_load_dwordx4 v[170:173], v[122:123], off
	global_load_dwordx4 v[166:169], v[124:125], off offset:256
	global_load_dwordx4 v[162:165], v[122:123], off offset:256
	v_lshl_add_u64 v[122:123], v[206:207], 0, v[222:223]
	global_load_dwordx4 v[122:125], v[122:123], off
	v_mul_f32_e32 v152, v152, v236
	v_mul_f32_e32 v153, v153, v236
	v_mul_f32_e32 v152, 0xbfb8aa3b, v152
	v_mul_f32_e32 v153, 0xbfb8aa3b, v153
	v_mul_f32_e32 v130, v130, v236
	v_mul_f32_e32 v131, v131, v236
	v_exp_f32_e32 v152, v152
	v_exp_f32_e32 v153, v153
	v_mul_f32_e32 v130, 0xbfb8aa3b, v130
	v_mul_f32_e32 v131, 0xbfb8aa3b, v131
	v_exp_f32_e32 v130, v130
	v_exp_f32_e32 v131, v131
	v_add_f32_e32 v152, 1.0, v152
	v_add_f32_e32 v153, 1.0, v153
	v_rcp_f32_e32 v152, v152
	v_rcp_f32_e32 v153, v153
	v_add_f32_e32 v130, 1.0, v130
	v_add_f32_e32 v131, 1.0, v131
	v_rcp_f32_e32 v130, v130
	v_rcp_f32_e32 v131, v131
	v_mul_f32_e32 v150, v150, v236
	v_mul_f32_e32 v151, v151, v236
	v_mul_f32_e32 v150, 0xbfb8aa3b, v150
	v_mul_f32_e32 v151, 0xbfb8aa3b, v151
	v_exp_f32_e32 v150, v150
	v_exp_f32_e32 v151, v151
	v_mul_f32_e32 v118, v118, v236
	v_mul_f32_e32 v119, v119, v236
	v_add_f32_e32 v150, 1.0, v150
	v_add_f32_e32 v151, 1.0, v151
	v_rcp_f32_e32 v150, v150
	v_rcp_f32_e32 v151, v151
	v_mul_f32_e32 v118, 0xbfb8aa3b, v118
	v_mul_f32_e32 v119, 0xbfb8aa3b, v119
	v_mul_f32_e32 v120, v120, v236
	v_mul_f32_e32 v121, v121, v236
	v_exp_f32_e32 v118, v118
	v_exp_f32_e32 v119, v119
	v_mul_f32_e32 v120, 0xbfb8aa3b, v120
	v_mul_f32_e32 v121, 0xbfb8aa3b, v121
	v_mul_f32_e32 v114, v114, v236
	v_mul_f32_e32 v115, v115, v236
	v_exp_f32_e32 v120, v120
	v_exp_f32_e32 v121, v121
	v_mul_f32_e32 v114, 0xbfb8aa3b, v114
	v_mul_f32_e32 v115, 0xbfb8aa3b, v115
	v_exp_f32_e32 v114, v114
	v_exp_f32_e32 v115, v115
	v_add_f32_e32 v118, 1.0, v118
	v_add_f32_e32 v119, 1.0, v119
	v_rcp_f32_e32 v118, v118
	v_rcp_f32_e32 v119, v119
	v_add_f32_e32 v120, 1.0, v120
	v_add_f32_e32 v121, 1.0, v121
	v_rcp_f32_e32 v120, v120
	v_rcp_f32_e32 v121, v121
	v_add_f32_e32 v114, 1.0, v114
	v_add_f32_e32 v115, 1.0, v115
	v_rcp_f32_e32 v114, v114
	v_rcp_f32_e32 v115, v115
	v_add_f32_e32 v210, v242, v243
	v_lshlrev_b32_e32 v242, 16, v186
	v_and_b32_e32 v243, 0xffff0000, v186
	v_lshlrev_b32_e32 v186, 16, v187
	v_and_b32_e32 v187, 0xffff0000, v187
	v_pk_fma_f32 v[152:153], v[152:153], v[186:187], v[190:191]
	v_lshlrev_b32_e32 v186, 16, v192
	v_and_b32_e32 v187, 0xffff0000, v192
	v_lshlrev_b32_e32 v190, 16, v188
	v_and_b32_e32 v191, 0xffff0000, v188
	v_pk_fma_f32 v[186:187], v[130:131], v[190:191], v[186:187]
	v_mul_f32_e32 v130, v132, v236
	v_mul_f32_e32 v131, v133, v236
	v_mul_f32_e32 v130, 0xbfb8aa3b, v130
	v_mul_f32_e32 v131, 0xbfb8aa3b, v131
	v_exp_f32_e32 v130, v130
	v_exp_f32_e32 v131, v131
	v_add_f32_e32 v211, v244, v245
	v_add_f32_e32 v210, v210, v211
	ds_bpermute_b32 v211, v229, v210
	v_add_f32_e32 v130, 1.0, v130
	v_add_f32_e32 v131, 1.0, v131
	v_rcp_f32_e32 v130, v130
	v_rcp_f32_e32 v131, v131
	s_waitcnt lgkmcnt(0)
	v_add_f32_e32 v230, v210, v211
	v_lshlrev_b64 v[210:211], 11, v[208:209]
	v_pk_fma_f32 v[150:151], v[150:151], v[242:243], v[238:239]
	v_lshlrev_b32_e32 v132, 16, v193
	v_and_b32_e32 v133, 0xffff0000, v193
	v_lshlrev_b32_e32 v188, 16, v189
	v_and_b32_e32 v189, 0xffff0000, v189
	v_pk_fma_f32 v[188:189], v[130:131], v[188:189], v[132:133]
	v_cvt_pk_bf16_f32 v130, v150, v151
	v_lshl_add_u64 v[150:151], s[92:93], 0, v[210:211]
	v_cvt_pk_bf16_f32 v131, v152, v153
	v_cvt_pk_bf16_f32 v132, v186, v187
	v_cvt_pk_bf16_f32 v133, v188, v189
	v_lshl_add_u64 v[150:151], v[204:205], 1, v[150:151]
	global_store_dwordx4 v[150:151], v[130:133], off
	v_lshlrev_b32_e32 v152, 16, v130
	v_lshlrev_b32_e32 v153, 16, v131
	v_and_b32_e32 v130, 0xffff0000, v130
	v_and_b32_e32 v131, 0xffff0000, v131
	v_mul_f32_e32 v130, v130, v130
	v_mul_f32_e32 v131, v131, v131
	v_lshlrev_b32_e32 v186, 16, v132
	v_and_b32_e32 v132, 0xffff0000, v132
	v_fmac_f32_e32 v130, v152, v152
	v_fmac_f32_e32 v131, v153, v153
	v_add_f32_e32 v130, v130, v131
	v_mul_f32_e32 v131, v132, v132
	v_lshlrev_b32_e32 v187, 16, v133
	v_and_b32_e32 v133, 0xffff0000, v133
	v_fmac_f32_e32 v131, v186, v186
	v_add_f32_e32 v130, v131, v130
	v_mul_f32_e32 v131, v133, v133
	v_fmac_f32_e32 v131, v187, v187
	v_add_f32_e32 v152, v131, v130
	v_lshlrev_b32_e32 v130, 16, v182
	v_and_b32_e32 v131, 0xffff0000, v182
	v_lshlrev_b32_e32 v132, 16, v178
	v_and_b32_e32 v133, 0xffff0000, v178
	v_pk_fma_f32 v[118:119], v[118:119], v[132:133], v[130:131]
	v_lshlrev_b32_e32 v130, 16, v183
	v_and_b32_e32 v131, 0xffff0000, v183
	v_lshlrev_b32_e32 v132, 16, v179
	v_and_b32_e32 v133, 0xffff0000, v179
	v_pk_fma_f32 v[120:121], v[120:121], v[132:133], v[130:131]
	v_lshlrev_b32_e32 v130, 16, v184
	v_and_b32_e32 v131, 0xffff0000, v184
	v_lshlrev_b32_e32 v132, 16, v180
	v_and_b32_e32 v133, 0xffff0000, v180
	v_pk_fma_f32 v[130:131], v[114:115], v[132:133], v[130:131]
	v_mul_f32_e32 v114, v116, v236
	v_mul_f32_e32 v115, v117, v236
	v_mul_f32_e32 v114, 0xbfb8aa3b, v114
	v_mul_f32_e32 v115, 0xbfb8aa3b, v115
	v_exp_f32_e32 v114, v114
	v_exp_f32_e32 v115, v115
	v_lshlrev_b32_e32 v116, 16, v185
	v_and_b32_e32 v117, 0xffff0000, v185
	v_add_f32_e32 v114, 1.0, v114
	v_add_f32_e32 v115, 1.0, v115
	v_rcp_f32_e32 v114, v114
	v_rcp_f32_e32 v115, v115
	v_lshlrev_b32_e32 v132, 16, v181
	v_and_b32_e32 v133, 0xffff0000, v181
	ds_bpermute_b32 v231, v228, v230
	v_pk_fma_f32 v[132:133], v[114:115], v[132:133], v[116:117]
	v_cvt_pk_bf16_f32 v114, v118, v119
	v_cvt_pk_bf16_f32 v115, v120, v121
	v_cvt_pk_bf16_f32 v116, v130, v131
	v_cvt_pk_bf16_f32 v117, v132, v133
	global_store_dwordx4 v[150:151], v[114:117], off offset:256
	v_lshlrev_b32_e32 v118, 16, v114
	v_lshlrev_b32_e32 v119, 16, v115
	v_and_b32_e32 v114, 0xffff0000, v114
	v_and_b32_e32 v115, 0xffff0000, v115
	v_mul_f32_e32 v114, v114, v114
	v_fmac_f32_e32 v114, v118, v118
	v_mul_f32_e32 v115, v115, v115
	v_lshlrev_b32_e32 v120, 16, v116
	v_and_b32_e32 v116, 0xffff0000, v116
	v_add_f32_e32 v114, v114, v152
	v_fmac_f32_e32 v115, v119, v119
	v_add_f32_e32 v114, v115, v114
	v_mul_f32_e32 v115, v116, v116
	v_lshlrev_b32_e32 v121, 16, v117
	v_and_b32_e32 v117, 0xffff0000, v117
	v_fmac_f32_e32 v115, v120, v120
	v_add_f32_e32 v114, v115, v114
	v_mul_f32_e32 v115, v117, v117
	v_fmac_f32_e32 v115, v121, v121
	v_add_f32_e32 v114, v115, v114
	ds_bpermute_b32 v115, v229, v114
	s_waitcnt lgkmcnt(0)
	v_add_f32_e32 v114, v114, v115
	ds_bpermute_b32 v115, v228, v114
	s_and_saveexec_b64 s[10:11], vcc
	s_cbranch_execz .LBB0_950
	s_lshl_b32 s20, s82, 2
	v_lshl_add_u64 v[116:117], s[4:5], 0, v[226:227]
	s_ashr_i32 s21, s20, 31
	v_lshl_add_u64 v[116:117], s[20:21], 2, v[116:117]
	s_lshl_b32 s76, s19, 2
	v_lshl_add_u64 v[116:117], v[116:117], 0, s[76:77]
	s_waitcnt lgkmcnt(0)
	v_add_f32_e32 v114, v114, v115
	global_store_dword v[116:117], v114, off
.LBB0_950:
	s_or_b64 exec, exec, s[10:11]
	s_waitcnt vmcnt(3)
	v_add_f32_e32 v122, v122, v123
	v_add_f32_e32 v123, v124, v125
	v_add_f32_e32 v122, v122, v123
	ds_bpermute_b32 v123, v229, v122
	s_waitcnt lgkmcnt(0)
	v_add_f32_e32 v234, v122, v123
	v_lshlrev_b64 v[122:123], 10, v[218:219]
	v_lshl_add_u64 v[122:123], v[122:123], 0, v[204:205]
	v_lshlrev_b64 v[122:123], 1, v[122:123]
	v_lshl_add_u64 v[124:125], s[88:89], 0, v[122:123]
	v_lshl_add_u64 v[122:123], s[62:63], 0, v[122:123]
	global_load_dwordx4 v[158:161], v[124:125], off
	global_load_dwordx4 v[154:157], v[122:123], off
	global_load_dwordx4 v[146:149], v[124:125], off offset:256
	global_load_dwordx4 v[142:145], v[122:123], off offset:256
	v_lshl_add_u64 v[122:123], v[206:207], 0, v[220:221]
	global_load_dwordx4 v[122:125], v[122:123], off
	ds_bpermute_b32 v235, v228, v234
	s_waitcnt lgkmcnt(0)
	v_add_f32_e32 v114, v234, v235
	v_fmamk_f32 v114, v114, 0x3a800000, v240
	v_rsq_f32_e32 v118, v114
	v_lshlrev_b32_e32 v116, 16, v170
	v_and_b32_e32 v117, 0xffff0000, v170
	v_mul_f32_e32 v110, v110, v118
	v_mul_f32_e32 v111, v111, v118
	v_mul_f32_e32 v110, 0xbfb8aa3b, v110
	v_mul_f32_e32 v111, 0xbfb8aa3b, v111
	v_mul_f32_e32 v112, v112, v118
	v_mul_f32_e32 v113, v113, v118
	v_exp_f32_e32 v114, v110
	v_exp_f32_e32 v111, v111
	v_mul_f32_e32 v112, 0xbfb8aa3b, v112
	v_mul_f32_e32 v113, 0xbfb8aa3b, v113
	v_mul_f32_e32 v106, v106, v118
	v_mul_f32_e32 v107, v107, v118
	v_exp_f32_e32 v112, v112
	v_exp_f32_e32 v113, v113
	v_mul_f32_e32 v106, 0xbfb8aa3b, v106
	v_mul_f32_e32 v107, 0xbfb8aa3b, v107
	v_exp_f32_e32 v106, v106
	v_exp_f32_e32 v107, v107
	v_mul_f32_e32 v108, v108, v118
	v_add_f32_e32 v114, 1.0, v114
	v_add_f32_e32 v111, 1.0, v111
	v_mul_f32_e32 v108, 0xbfb8aa3b, v108
	v_rcp_f32_e32 v114, v114
	s_waitcnt lgkmcnt(0)
	v_rcp_f32_e32 v115, v111
	v_add_f32_e32 v112, 1.0, v112
	v_add_f32_e32 v113, 1.0, v113
	v_exp_f32_e32 v119, v108
	v_mul_f32_e32 v108, v109, v118
	v_rcp_f32_e32 v112, v112
	v_rcp_f32_e32 v113, v113
	v_add_f32_e32 v106, 1.0, v106
	v_add_f32_e32 v107, 1.0, v107
	v_mul_f32_e32 v108, 0xbfb8aa3b, v108
	v_rcp_f32_e32 v106, v106
	v_rcp_f32_e32 v107, v107
	v_exp_f32_e32 v120, v108
	v_lshlrev_b32_e32 v110, 16, v174
	v_and_b32_e32 v111, 0xffff0000, v174
	v_pk_fma_f32 v[110:111], v[114:115], v[116:117], v[110:111]
	v_lshlrev_b32_e32 v114, 16, v175
	v_and_b32_e32 v115, 0xffff0000, v175
	v_lshlrev_b32_e32 v116, 16, v171
	v_and_b32_e32 v117, 0xffff0000, v171
	v_pk_fma_f32 v[112:113], v[112:113], v[116:117], v[114:115]
	v_lshlrev_b32_e32 v114, 16, v176
	v_and_b32_e32 v115, 0xffff0000, v176
	v_lshlrev_b32_e32 v116, 16, v172
	v_and_b32_e32 v117, 0xffff0000, v172
	v_pk_fma_f32 v[108:109], v[106:107], v[116:117], v[114:115]
	v_add_f32_e32 v106, 1.0, v119
	v_add_f32_e32 v107, 1.0, v120
	v_rcp_f32_e32 v106, v106
	v_rcp_f32_e32 v107, v107
	v_lshlrev_b32_e32 v114, 16, v177
	v_and_b32_e32 v115, 0xffff0000, v177
	v_lshlrev_b32_e32 v116, 16, v173
	v_and_b32_e32 v117, 0xffff0000, v173
	v_pk_fma_f32 v[114:115], v[106:107], v[116:117], v[114:115]
	v_cvt_pk_bf16_f32 v106, v110, v111
	v_mul_f32_e32 v102, v102, v118
	v_mul_f32_e32 v103, v103, v118
	v_cvt_pk_bf16_f32 v107, v112, v113
	v_and_b32_e32 v111, 0xffff0000, v106
	v_mul_f32_e32 v102, 0xbfb8aa3b, v102
	v_mul_f32_e32 v103, 0xbfb8aa3b, v103
	v_mul_f32_e32 v104, v104, v118
	v_mul_f32_e32 v105, v105, v118
	v_lshlrev_b32_e32 v110, 16, v106
	v_and_b32_e32 v113, 0xffff0000, v107
	v_mul_f32_e32 v111, v111, v111
	v_exp_f32_e32 v102, v102
	v_exp_f32_e32 v103, v103
	v_mul_f32_e32 v104, 0xbfb8aa3b, v104
	v_mul_f32_e32 v105, 0xbfb8aa3b, v105
	v_cvt_pk_bf16_f32 v108, v108, v109
	v_lshlrev_b32_e32 v112, 16, v107
	v_fmac_f32_e32 v111, v110, v110
	v_mul_f32_e32 v110, v113, v113
	v_exp_f32_e32 v104, v104
	v_exp_f32_e32 v105, v105
	v_cvt_pk_bf16_f32 v109, v114, v115
	v_and_b32_e32 v115, 0xffff0000, v108
	v_fmac_f32_e32 v110, v112, v112
	v_mul_f32_e32 v98, v98, v118
	v_lshlrev_b32_e32 v114, 16, v108
	v_add_f32_e32 v110, v111, v110
	v_mul_f32_e32 v111, v115, v115
	v_mul_f32_e32 v98, 0xbfb8aa3b, v98
	v_and_b32_e32 v117, 0xffff0000, v109
	v_fmac_f32_e32 v111, v114, v114
	v_add_f32_e32 v102, 1.0, v102
	v_add_f32_e32 v103, 1.0, v103
	v_exp_f32_e32 v115, v98
	v_mul_f32_e32 v98, v99, v118
	v_lshlrev_b32_e32 v116, 16, v109
	v_add_f32_e32 v110, v111, v110
	v_mul_f32_e32 v111, v117, v117
	v_rcp_f32_e32 v102, v102
	v_rcp_f32_e32 v103, v103
	v_add_f32_e32 v104, 1.0, v104
	v_add_f32_e32 v105, 1.0, v105
	v_mul_f32_e32 v98, 0xbfb8aa3b, v98
	v_mul_f32_e32 v100, v100, v118
	v_mul_f32_e32 v101, v101, v118
	v_fmac_f32_e32 v111, v116, v116
	v_rcp_f32_e32 v104, v104
	v_rcp_f32_e32 v105, v105
	v_exp_f32_e32 v116, v98
	v_mul_f32_e32 v100, 0xbfb8aa3b, v100
	v_mul_f32_e32 v101, 0xbfb8aa3b, v101
	v_exp_f32_e32 v100, v100
	v_exp_f32_e32 v101, v101
	v_add_f32_e32 v114, v111, v110
	v_lshlrev_b32_e32 v110, 16, v166
	v_and_b32_e32 v111, 0xffff0000, v166
	v_lshlrev_b32_e32 v112, 16, v162
	v_and_b32_e32 v113, 0xffff0000, v162
	v_pk_fma_f32 v[102:103], v[102:103], v[112:113], v[110:111]
	v_lshlrev_b32_e32 v110, 16, v167
	v_and_b32_e32 v111, 0xffff0000, v167
	v_lshlrev_b32_e32 v112, 16, v163
	v_and_b32_e32 v113, 0xffff0000, v163
	v_pk_fma_f32 v[98:99], v[104:105], v[112:113], v[110:111]
	v_add_f32_e32 v104, 1.0, v115
	v_add_f32_e32 v105, 1.0, v116
	v_rcp_f32_e32 v104, v104
	v_rcp_f32_e32 v105, v105
	v_add_f32_e32 v100, 1.0, v100
	v_add_f32_e32 v101, 1.0, v101
	v_rcp_f32_e32 v100, v100
	v_rcp_f32_e32 v101, v101
	v_lshlrev_b32_e32 v110, 16, v168
	v_and_b32_e32 v111, 0xffff0000, v168
	v_lshlrev_b32_e32 v112, 16, v164
	v_and_b32_e32 v113, 0xffff0000, v164
	v_pk_fma_f32 v[104:105], v[104:105], v[112:113], v[110:111]
	v_lshlrev_b32_e32 v110, 16, v169
	v_and_b32_e32 v111, 0xffff0000, v169
	v_lshlrev_b32_e32 v112, 16, v165
	v_and_b32_e32 v113, 0xffff0000, v165
	v_pk_fma_f32 v[110:111], v[100:101], v[112:113], v[110:111]
	v_cvt_pk_bf16_f32 v100, v102, v103
	v_cvt_pk_bf16_f32 v101, v98, v99
	v_and_b32_e32 v99, 0xffff0000, v100
	v_lshlrev_b32_e32 v98, 16, v100
	v_mul_f32_e32 v99, v99, v99
	v_cvt_pk_bf16_f32 v102, v104, v105
	v_and_b32_e32 v105, 0xffff0000, v101
	v_fmac_f32_e32 v99, v98, v98
	v_lshlrev_b32_e32 v104, 16, v101
	v_add_f32_e32 v98, v99, v114
	v_mul_f32_e32 v99, v105, v105
	v_cvt_pk_bf16_f32 v103, v110, v111
	v_and_b32_e32 v111, 0xffff0000, v102
	v_fmac_f32_e32 v99, v104, v104
	v_lshlrev_b32_e32 v110, 16, v102
	v_add_f32_e32 v98, v99, v98
	v_mul_f32_e32 v99, v111, v111
	v_and_b32_e32 v113, 0xffff0000, v103
	v_fmac_f32_e32 v99, v110, v110
	v_lshlrev_b32_e32 v112, 16, v103
	v_add_f32_e32 v98, v99, v98
	v_mul_f32_e32 v99, v113, v113
	v_fmac_f32_e32 v99, v112, v112
	v_add_f32_e32 v98, v99, v98
	ds_bpermute_b32 v99, v229, v98
	v_lshlrev_b64 v[104:105], 11, v[224:225]
	v_lshl_add_u64 v[104:105], s[92:93], 0, v[104:105]
	v_lshl_add_u64 v[104:105], v[204:205], 1, v[104:105]
	global_store_dwordx4 v[104:105], v[106:109], off
	global_store_dwordx4 v[104:105], v[100:103], off offset:256
	s_waitcnt lgkmcnt(0)
	v_add_f32_e32 v98, v98, v99
	ds_bpermute_b32 v99, v228, v98
	s_and_saveexec_b64 s[10:11], vcc
	s_cbranch_execz .LBB0_952
	s_lshl_b32 s20, s82, 2
	v_lshl_add_u64 v[100:101], s[4:5], 0, v[222:223]
	s_ashr_i32 s21, s20, 31
	v_lshl_add_u64 v[100:101], s[20:21], 2, v[100:101]
	s_lshl_b32 s76, s19, 2
	v_lshl_add_u64 v[100:101], v[100:101], 0, s[76:77]
	s_waitcnt lgkmcnt(0)
	v_add_f32_e32 v98, v98, v99
	global_store_dword v[100:101], v98, off
.LBB0_952:
	s_or_b64 exec, exec, s[10:11]
	s_waitcnt vmcnt(3)
	v_add_f32_e32 v122, v122, v123
	v_add_f32_e32 v123, v124, v125
	v_add_f32_e32 v122, v122, v123
	ds_bpermute_b32 v123, v229, v122
	s_waitcnt lgkmcnt(0)
	v_add_f32_e32 v232, v122, v123
	v_lshlrev_b64 v[122:123], 10, v[214:215]
	v_lshl_add_u64 v[122:123], v[122:123], 0, v[204:205]
	v_lshlrev_b64 v[122:123], 1, v[122:123]
	v_lshl_add_u64 v[124:125], s[88:89], 0, v[122:123]
	v_lshl_add_u64 v[122:123], s[62:63], 0, v[122:123]
	global_load_dwordx4 v[138:141], v[124:125], off
	global_load_dwordx4 v[134:137], v[122:123], off
	global_load_dwordx4 v[126:129], v[124:125], off offset:256
	s_nop 0
	global_load_dwordx4 v[122:125], v[122:123], off offset:256
	ds_bpermute_b32 v233, v228, v232
	s_waitcnt lgkmcnt(0)
	v_add_f32_e32 v98, v232, v233
	v_fmamk_f32 v98, v98, 0x3a800000, v240
	v_rsq_f32_e32 v102, v98
	v_lshlrev_b32_e32 v100, 16, v154
	v_and_b32_e32 v101, 0xffff0000, v154
	v_mul_f32_e32 v94, v94, v102
	v_mul_f32_e32 v95, v95, v102
	v_mul_f32_e32 v94, 0xbfb8aa3b, v94
	v_mul_f32_e32 v95, 0xbfb8aa3b, v95
	v_mul_f32_e32 v96, v96, v102
	v_mul_f32_e32 v97, v97, v102
	v_exp_f32_e32 v98, v94
	v_exp_f32_e32 v95, v95
	v_mul_f32_e32 v96, 0xbfb8aa3b, v96
	v_mul_f32_e32 v97, 0xbfb8aa3b, v97
	v_mul_f32_e32 v90, v90, v102
	v_mul_f32_e32 v91, v91, v102
	v_exp_f32_e32 v96, v96
	v_exp_f32_e32 v97, v97
	v_mul_f32_e32 v90, 0xbfb8aa3b, v90
	v_mul_f32_e32 v91, 0xbfb8aa3b, v91
	v_exp_f32_e32 v90, v90
	v_exp_f32_e32 v91, v91
	v_mul_f32_e32 v92, v92, v102
	v_add_f32_e32 v98, 1.0, v98
	v_add_f32_e32 v95, 1.0, v95
	v_mul_f32_e32 v92, 0xbfb8aa3b, v92
	v_rcp_f32_e32 v98, v98
	s_waitcnt lgkmcnt(0)
	v_rcp_f32_e32 v99, v95
	v_add_f32_e32 v96, 1.0, v96
	v_add_f32_e32 v97, 1.0, v97
	v_exp_f32_e32 v103, v92
	v_mul_f32_e32 v92, v93, v102
	v_rcp_f32_e32 v96, v96
	v_rcp_f32_e32 v97, v97
	v_add_f32_e32 v90, 1.0, v90
	v_add_f32_e32 v91, 1.0, v91
	v_mul_f32_e32 v92, 0xbfb8aa3b, v92
	v_rcp_f32_e32 v90, v90
	v_rcp_f32_e32 v91, v91
	v_exp_f32_e32 v104, v92
	v_lshlrev_b32_e32 v94, 16, v158
	v_and_b32_e32 v95, 0xffff0000, v158
	v_pk_fma_f32 v[94:95], v[98:99], v[100:101], v[94:95]
	v_lshlrev_b32_e32 v98, 16, v159
	v_and_b32_e32 v99, 0xffff0000, v159
	v_lshlrev_b32_e32 v100, 16, v155
	v_and_b32_e32 v101, 0xffff0000, v155
	v_pk_fma_f32 v[96:97], v[96:97], v[100:101], v[98:99]
	v_lshlrev_b32_e32 v98, 16, v160
	v_and_b32_e32 v99, 0xffff0000, v160
	v_lshlrev_b32_e32 v100, 16, v156
	v_and_b32_e32 v101, 0xffff0000, v156
	v_pk_fma_f32 v[92:93], v[90:91], v[100:101], v[98:99]
	v_add_f32_e32 v90, 1.0, v103
	v_add_f32_e32 v91, 1.0, v104
	v_rcp_f32_e32 v90, v90
	v_rcp_f32_e32 v91, v91
	v_lshlrev_b32_e32 v98, 16, v161
	v_and_b32_e32 v99, 0xffff0000, v161
	v_lshlrev_b32_e32 v100, 16, v157
	v_and_b32_e32 v101, 0xffff0000, v157
	v_pk_fma_f32 v[98:99], v[90:91], v[100:101], v[98:99]
	v_cvt_pk_bf16_f32 v90, v94, v95
	v_mul_f32_e32 v86, v86, v102
	v_mul_f32_e32 v87, v87, v102
	v_cvt_pk_bf16_f32 v91, v96, v97
	v_and_b32_e32 v95, 0xffff0000, v90
	v_mul_f32_e32 v86, 0xbfb8aa3b, v86
	v_mul_f32_e32 v87, 0xbfb8aa3b, v87
	v_mul_f32_e32 v88, v88, v102
	v_mul_f32_e32 v89, v89, v102
	v_lshlrev_b32_e32 v94, 16, v90
	v_and_b32_e32 v97, 0xffff0000, v91
	v_mul_f32_e32 v95, v95, v95
	v_exp_f32_e32 v86, v86
	v_exp_f32_e32 v87, v87
	v_mul_f32_e32 v88, 0xbfb8aa3b, v88
	v_mul_f32_e32 v89, 0xbfb8aa3b, v89
	v_cvt_pk_bf16_f32 v92, v92, v93
	v_lshlrev_b32_e32 v96, 16, v91
	v_fmac_f32_e32 v95, v94, v94
	v_mul_f32_e32 v94, v97, v97
	v_exp_f32_e32 v88, v88
	v_exp_f32_e32 v89, v89
	v_cvt_pk_bf16_f32 v93, v98, v99
	v_and_b32_e32 v99, 0xffff0000, v92
	v_fmac_f32_e32 v94, v96, v96
	v_mul_f32_e32 v82, v82, v102
	v_lshlrev_b32_e32 v98, 16, v92
	v_add_f32_e32 v94, v95, v94
	v_mul_f32_e32 v95, v99, v99
	v_mul_f32_e32 v82, 0xbfb8aa3b, v82
	v_and_b32_e32 v101, 0xffff0000, v93
	v_fmac_f32_e32 v95, v98, v98
	v_add_f32_e32 v86, 1.0, v86
	v_add_f32_e32 v87, 1.0, v87
	v_exp_f32_e32 v99, v82
	v_mul_f32_e32 v82, v83, v102
	v_lshlrev_b32_e32 v100, 16, v93
	v_add_f32_e32 v94, v95, v94
	v_mul_f32_e32 v95, v101, v101
	v_rcp_f32_e32 v86, v86
	v_rcp_f32_e32 v87, v87
	v_add_f32_e32 v88, 1.0, v88
	v_add_f32_e32 v89, 1.0, v89
	v_mul_f32_e32 v82, 0xbfb8aa3b, v82
	v_mul_f32_e32 v84, v84, v102
	v_mul_f32_e32 v85, v85, v102
	v_fmac_f32_e32 v95, v100, v100
	v_rcp_f32_e32 v88, v88
	v_rcp_f32_e32 v89, v89
	v_exp_f32_e32 v100, v82
	v_mul_f32_e32 v84, 0xbfb8aa3b, v84
	v_mul_f32_e32 v85, 0xbfb8aa3b, v85
	v_exp_f32_e32 v84, v84
	v_exp_f32_e32 v85, v85
	v_add_f32_e32 v98, v95, v94
	v_lshlrev_b32_e32 v94, 16, v146
	v_and_b32_e32 v95, 0xffff0000, v146
	v_lshlrev_b32_e32 v96, 16, v142
	v_and_b32_e32 v97, 0xffff0000, v142
	v_pk_fma_f32 v[86:87], v[86:87], v[96:97], v[94:95]
	v_lshlrev_b32_e32 v94, 16, v147
	v_and_b32_e32 v95, 0xffff0000, v147
	v_lshlrev_b32_e32 v96, 16, v143
	v_and_b32_e32 v97, 0xffff0000, v143
	v_pk_fma_f32 v[82:83], v[88:89], v[96:97], v[94:95]
	v_add_f32_e32 v88, 1.0, v99
	v_add_f32_e32 v89, 1.0, v100
	v_rcp_f32_e32 v88, v88
	v_rcp_f32_e32 v89, v89
	v_add_f32_e32 v84, 1.0, v84
	v_add_f32_e32 v85, 1.0, v85
	v_rcp_f32_e32 v84, v84
	v_rcp_f32_e32 v85, v85
	v_lshlrev_b32_e32 v94, 16, v148
	v_and_b32_e32 v95, 0xffff0000, v148
	v_lshlrev_b32_e32 v96, 16, v144
	v_and_b32_e32 v97, 0xffff0000, v144
	v_pk_fma_f32 v[88:89], v[88:89], v[96:97], v[94:95]
	v_lshlrev_b32_e32 v94, 16, v149
	v_and_b32_e32 v95, 0xffff0000, v149
	v_lshlrev_b32_e32 v96, 16, v145
	v_and_b32_e32 v97, 0xffff0000, v145
	v_pk_fma_f32 v[94:95], v[84:85], v[96:97], v[94:95]
	v_cvt_pk_bf16_f32 v84, v86, v87
	v_cvt_pk_bf16_f32 v85, v82, v83
	v_and_b32_e32 v83, 0xffff0000, v84
	v_lshlrev_b32_e32 v82, 16, v84
	v_mul_f32_e32 v83, v83, v83
	v_cvt_pk_bf16_f32 v86, v88, v89
	v_and_b32_e32 v89, 0xffff0000, v85
	v_fmac_f32_e32 v83, v82, v82
	v_lshlrev_b32_e32 v88, 16, v85
	v_add_f32_e32 v82, v83, v98
	v_mul_f32_e32 v83, v89, v89
	v_cvt_pk_bf16_f32 v87, v94, v95
	v_and_b32_e32 v95, 0xffff0000, v86
	v_fmac_f32_e32 v83, v88, v88
	v_lshlrev_b32_e32 v94, 16, v86
	v_add_f32_e32 v82, v83, v82
	v_mul_f32_e32 v83, v95, v95
	v_and_b32_e32 v97, 0xffff0000, v87
	v_fmac_f32_e32 v83, v94, v94
	v_lshlrev_b32_e32 v96, 16, v87
	v_add_f32_e32 v82, v83, v82
	v_mul_f32_e32 v83, v97, v97
	v_fmac_f32_e32 v83, v96, v96
	v_add_f32_e32 v82, v83, v82
	ds_bpermute_b32 v83, v229, v82
	v_lshlrev_b64 v[88:89], 11, v[218:219]
	v_lshl_add_u64 v[88:89], s[92:93], 0, v[88:89]
	v_lshl_add_u64 v[88:89], v[204:205], 1, v[88:89]
	global_store_dwordx4 v[88:89], v[90:93], off
	global_store_dwordx4 v[88:89], v[84:87], off offset:256
	s_waitcnt lgkmcnt(0)
	v_add_f32_e32 v82, v82, v83
	ds_bpermute_b32 v83, v228, v82
	s_and_saveexec_b64 s[10:11], vcc
	s_cbranch_execz .LBB0_954
	s_lshl_b32 s20, s82, 2
	v_lshl_add_u64 v[84:85], s[4:5], 0, v[220:221]
	s_ashr_i32 s21, s20, 31
	v_lshl_add_u64 v[84:85], s[20:21], 2, v[84:85]
	s_lshl_b32 s76, s19, 2
	v_lshl_add_u64 v[84:85], v[84:85], 0, s[76:77]
	s_waitcnt lgkmcnt(0)
	v_add_f32_e32 v82, v82, v83
	global_store_dword v[84:85], v82, off
.LBB0_954:
	s_or_b64 exec, exec, s[10:11]
	s_waitcnt vmcnt(3)
	v_add_f32_e32 v82, v230, v231
	v_fmamk_f32 v82, v82, 0x3a800000, v240
	v_rsq_f32_e32 v86, v82
	v_lshlrev_b32_e32 v84, 16, v134
	v_and_b32_e32 v85, 0xffff0000, v134
	v_mul_f32_e32 v78, v78, v86
	v_mul_f32_e32 v79, v79, v86
	v_mul_f32_e32 v78, 0xbfb8aa3b, v78
	v_mul_f32_e32 v79, 0xbfb8aa3b, v79
	v_mul_f32_e32 v80, v80, v86
	v_mul_f32_e32 v81, v81, v86
	v_exp_f32_e32 v82, v78
	v_exp_f32_e32 v79, v79
	v_mul_f32_e32 v80, 0xbfb8aa3b, v80
	v_mul_f32_e32 v81, 0xbfb8aa3b, v81
	v_mul_f32_e32 v74, v74, v86
	v_mul_f32_e32 v75, v75, v86
	v_exp_f32_e32 v80, v80
	v_exp_f32_e32 v81, v81
	v_mul_f32_e32 v74, 0xbfb8aa3b, v74
	v_mul_f32_e32 v75, 0xbfb8aa3b, v75
	v_exp_f32_e32 v74, v74
	v_exp_f32_e32 v75, v75
	v_mul_f32_e32 v76, v76, v86
	v_add_f32_e32 v82, 1.0, v82
	v_add_f32_e32 v79, 1.0, v79
	v_mul_f32_e32 v76, 0xbfb8aa3b, v76
	v_rcp_f32_e32 v82, v82
	s_waitcnt lgkmcnt(0)
	v_rcp_f32_e32 v83, v79
	v_add_f32_e32 v80, 1.0, v80
	v_add_f32_e32 v81, 1.0, v81
	v_exp_f32_e32 v87, v76
	v_mul_f32_e32 v76, v77, v86
	v_rcp_f32_e32 v80, v80
	v_rcp_f32_e32 v81, v81
	v_add_f32_e32 v74, 1.0, v74
	v_add_f32_e32 v75, 1.0, v75
	v_mul_f32_e32 v76, 0xbfb8aa3b, v76
	v_rcp_f32_e32 v74, v74
	v_rcp_f32_e32 v75, v75
	v_exp_f32_e32 v88, v76
	v_lshlrev_b32_e32 v78, 16, v138
	v_and_b32_e32 v79, 0xffff0000, v138
	v_pk_fma_f32 v[78:79], v[82:83], v[84:85], v[78:79]
	v_lshlrev_b32_e32 v82, 16, v139
	v_and_b32_e32 v83, 0xffff0000, v139
	v_lshlrev_b32_e32 v84, 16, v135
	v_and_b32_e32 v85, 0xffff0000, v135
	v_pk_fma_f32 v[80:81], v[80:81], v[84:85], v[82:83]
	v_lshlrev_b32_e32 v82, 16, v140
	v_and_b32_e32 v83, 0xffff0000, v140
	v_lshlrev_b32_e32 v84, 16, v136
	v_and_b32_e32 v85, 0xffff0000, v136
	v_pk_fma_f32 v[76:77], v[74:75], v[84:85], v[82:83]
	v_add_f32_e32 v74, 1.0, v87
	v_add_f32_e32 v75, 1.0, v88
	v_rcp_f32_e32 v74, v74
	v_rcp_f32_e32 v75, v75
	v_lshlrev_b32_e32 v82, 16, v141
	v_and_b32_e32 v83, 0xffff0000, v141
	v_lshlrev_b32_e32 v84, 16, v137
	v_and_b32_e32 v85, 0xffff0000, v137
	v_pk_fma_f32 v[82:83], v[74:75], v[84:85], v[82:83]
	v_cvt_pk_bf16_f32 v74, v78, v79
	v_mul_f32_e32 v70, v70, v86
	v_mul_f32_e32 v71, v71, v86
	v_cvt_pk_bf16_f32 v75, v80, v81
	v_and_b32_e32 v79, 0xffff0000, v74
	v_mul_f32_e32 v70, 0xbfb8aa3b, v70
	v_mul_f32_e32 v71, 0xbfb8aa3b, v71
	v_mul_f32_e32 v72, v72, v86
	v_mul_f32_e32 v73, v73, v86
	v_lshlrev_b32_e32 v78, 16, v74
	v_and_b32_e32 v81, 0xffff0000, v75
	v_mul_f32_e32 v79, v79, v79
	v_exp_f32_e32 v70, v70
	v_exp_f32_e32 v71, v71
	v_mul_f32_e32 v72, 0xbfb8aa3b, v72
	v_mul_f32_e32 v73, 0xbfb8aa3b, v73
	v_cvt_pk_bf16_f32 v76, v76, v77
	v_lshlrev_b32_e32 v80, 16, v75
	v_fmac_f32_e32 v79, v78, v78
	v_mul_f32_e32 v78, v81, v81
	v_exp_f32_e32 v72, v72
	v_exp_f32_e32 v73, v73
	v_cvt_pk_bf16_f32 v77, v82, v83
	v_and_b32_e32 v83, 0xffff0000, v76
	v_fmac_f32_e32 v78, v80, v80
	v_mul_f32_e32 v66, v66, v86
	v_lshlrev_b32_e32 v82, 16, v76
	v_add_f32_e32 v78, v79, v78
	v_mul_f32_e32 v79, v83, v83
	v_mul_f32_e32 v66, 0xbfb8aa3b, v66
	v_and_b32_e32 v85, 0xffff0000, v77
	v_fmac_f32_e32 v79, v82, v82
	v_add_f32_e32 v70, 1.0, v70
	v_add_f32_e32 v71, 1.0, v71
	v_exp_f32_e32 v83, v66
	v_mul_f32_e32 v66, v67, v86
	v_lshlrev_b32_e32 v84, 16, v77
	v_add_f32_e32 v78, v79, v78
	v_mul_f32_e32 v79, v85, v85
	v_rcp_f32_e32 v70, v70
	v_rcp_f32_e32 v71, v71
	v_add_f32_e32 v72, 1.0, v72
	v_add_f32_e32 v73, 1.0, v73
	v_mul_f32_e32 v66, 0xbfb8aa3b, v66
	v_mul_f32_e32 v68, v68, v86
	v_mul_f32_e32 v69, v69, v86
	v_fmac_f32_e32 v79, v84, v84
	v_rcp_f32_e32 v72, v72
	v_rcp_f32_e32 v73, v73
	v_exp_f32_e32 v84, v66
	v_mul_f32_e32 v68, 0xbfb8aa3b, v68
	v_mul_f32_e32 v69, 0xbfb8aa3b, v69
	v_exp_f32_e32 v68, v68
	v_exp_f32_e32 v69, v69
	v_add_f32_e32 v82, v79, v78
	v_lshlrev_b32_e32 v78, 16, v126
	v_and_b32_e32 v79, 0xffff0000, v126
	v_lshlrev_b32_e32 v80, 16, v122
	v_and_b32_e32 v81, 0xffff0000, v122
	v_pk_fma_f32 v[70:71], v[70:71], v[80:81], v[78:79]
	v_lshlrev_b32_e32 v78, 16, v127
	v_and_b32_e32 v79, 0xffff0000, v127
	v_lshlrev_b32_e32 v80, 16, v123
	v_and_b32_e32 v81, 0xffff0000, v123
	v_pk_fma_f32 v[66:67], v[72:73], v[80:81], v[78:79]
	v_add_f32_e32 v72, 1.0, v83
	v_add_f32_e32 v73, 1.0, v84
	v_rcp_f32_e32 v72, v72
	v_rcp_f32_e32 v73, v73
	v_add_f32_e32 v68, 1.0, v68
	v_add_f32_e32 v69, 1.0, v69
	v_rcp_f32_e32 v68, v68
	v_rcp_f32_e32 v69, v69
	v_lshlrev_b32_e32 v78, 16, v128
	v_and_b32_e32 v79, 0xffff0000, v128
	v_lshlrev_b32_e32 v80, 16, v124
	v_and_b32_e32 v81, 0xffff0000, v124
	v_pk_fma_f32 v[72:73], v[72:73], v[80:81], v[78:79]
	v_lshlrev_b32_e32 v78, 16, v129
	v_and_b32_e32 v79, 0xffff0000, v129
	v_lshlrev_b32_e32 v80, 16, v125
	v_and_b32_e32 v81, 0xffff0000, v125
	v_pk_fma_f32 v[78:79], v[68:69], v[80:81], v[78:79]
	v_cvt_pk_bf16_f32 v68, v70, v71
	v_cvt_pk_bf16_f32 v69, v66, v67
	v_and_b32_e32 v67, 0xffff0000, v68
	v_lshlrev_b32_e32 v66, 16, v68
	v_mul_f32_e32 v67, v67, v67
	v_cvt_pk_bf16_f32 v70, v72, v73
	v_and_b32_e32 v73, 0xffff0000, v69
	v_fmac_f32_e32 v67, v66, v66
	v_lshlrev_b32_e32 v72, 16, v69
	v_add_f32_e32 v66, v67, v82
	v_mul_f32_e32 v67, v73, v73
	v_cvt_pk_bf16_f32 v71, v78, v79
	v_and_b32_e32 v79, 0xffff0000, v70
	v_fmac_f32_e32 v67, v72, v72
	v_lshlrev_b32_e32 v78, 16, v70
	v_add_f32_e32 v66, v67, v66
	v_mul_f32_e32 v67, v79, v79
	v_and_b32_e32 v81, 0xffff0000, v71
	v_fmac_f32_e32 v67, v78, v78
	v_lshlrev_b32_e32 v80, 16, v71
	v_add_f32_e32 v66, v67, v66
	v_mul_f32_e32 v67, v81, v81
	v_fmac_f32_e32 v67, v80, v80
	v_add_f32_e32 v66, v67, v66
	ds_bpermute_b32 v67, v229, v66
	v_lshlrev_b64 v[72:73], 11, v[214:215]
	v_lshl_add_u64 v[72:73], s[92:93], 0, v[72:73]
	v_lshl_add_u64 v[72:73], v[204:205], 1, v[72:73]
	global_store_dwordx4 v[72:73], v[74:77], off
	global_store_dwordx4 v[72:73], v[68:71], off offset:256
	s_waitcnt lgkmcnt(0)
	v_add_f32_e32 v66, v66, v67
	ds_bpermute_b32 v67, v228, v66
	s_and_saveexec_b64 s[10:11], vcc
	s_cbranch_execz .LBB0_956
	s_lshl_b32 s20, s82, 2
	v_lshl_add_u64 v[68:69], s[4:5], 0, v[216:217]
	s_ashr_i32 s21, s20, 31
	v_lshl_add_u64 v[68:69], s[20:21], 2, v[68:69]
	s_lshl_b32 s76, s19, 2
	v_lshl_add_u64 v[68:69], v[68:69], 0, s[76:77]
	s_waitcnt lgkmcnt(0)
	v_add_f32_e32 v66, v66, v67
	global_store_dword v[68:69], v66, off
.LBB0_956:
	s_or_b64 exec, exec, s[10:11]
	v_add_u32_e32 v144, 0x80, v208
	v_ashrrev_i32_e32 v145, 31, v144
	s_waitcnt lgkmcnt(0)
	v_lshlrev_b64 v[66:67], 10, v[144:145]
	v_lshl_add_u64 v[66:67], v[66:67], 0, v[204:205]
	v_lshlrev_b64 v[66:67], 1, v[66:67]
	v_lshl_add_u64 v[68:69], s[88:89], 0, v[66:67]
	v_lshl_add_u64 v[66:67], s[62:63], 0, v[66:67]
	v_lshlrev_b64 v[142:143], 6, v[144:145]
	v_add_u32_e32 v140, 0x90, v208
	v_ashrrev_i32_e32 v141, 31, v140
	v_lshlrev_b64 v[138:139], 6, v[140:141]
	v_add_u32_e32 v134, 0xa0, v208
	v_ashrrev_i32_e32 v135, 31, v134
	v_lshlrev_b64 v[136:137], 6, v[134:135]
	v_add_u32_e32 v130, 0xb0, v208
	v_ashrrev_i32_e32 v131, 31, v130
	v_lshlrev_b64 v[132:133], 6, v[130:131]
	v_lshl_add_u64 v[146:147], v[206:207], 0, v[132:133]
	v_lshlrev_b64 v[144:145], 11, v[144:145]
	global_load_dwordx4 v[154:157], v[146:147], off
	global_load_dwordx4 v[126:129], v[68:69], off
	global_load_dwordx4 v[122:125], v[66:67], off
	global_load_dwordx4 v[118:121], v[68:69], off offset:256
	global_load_dwordx4 v[114:117], v[66:67], off offset:256
	v_lshl_add_u64 v[66:67], v[206:207], 0, v[142:143]
	global_load_dwordx4 v[66:69], v[66:67], off
	s_waitcnt vmcnt(0)
	v_mov_b32_e32 v70, v67
	v_mov_b32_e32 v71, v68
	v_mov_b32_e32 v67, v69
	v_pk_add_f32 v[66:67], v[70:71], v[66:67]
	s_nop 0
	v_add_f32_e32 v66, v66, v67
	ds_bpermute_b32 v67, v229, v66
	s_waitcnt lgkmcnt(0)
	v_add_f32_e32 v66, v66, v67
	ds_bpermute_b32 v67, v228, v66
	s_waitcnt lgkmcnt(0)
	v_add_f32_e32 v66, v66, v67
	v_fmamk_f32 v66, v66, 0x3a800000, v240
	v_rsq_f32_e32 v152, v66
	v_lshlrev_b64 v[66:67], 10, v[140:141]
	v_lshl_add_u64 v[66:67], v[66:67], 0, v[204:205]
	v_lshlrev_b64 v[66:67], 1, v[66:67]
	v_lshl_add_u64 v[68:69], s[88:89], 0, v[66:67]
	v_lshl_add_u64 v[66:67], s[62:63], 0, v[66:67]
	global_load_dwordx4 v[110:113], v[68:69], off
	global_load_dwordx4 v[106:109], v[66:67], off
	global_load_dwordx4 v[102:105], v[68:69], off offset:256
	global_load_dwordx4 v[98:101], v[66:67], off offset:256
	v_lshl_add_u64 v[66:67], v[206:207], 0, v[138:139]
	global_load_dwordx4 v[66:69], v[66:67], off
	v_mul_f32_e32 v64, v64, v152
	v_mul_f32_e32 v65, v65, v152
	v_mul_f32_e32 v64, 0xbfb8aa3b, v64
	v_mul_f32_e32 v65, 0xbfb8aa3b, v65
	v_mul_f32_e32 v58, v58, v152
	v_mul_f32_e32 v59, v59, v152
	v_exp_f32_e32 v64, v64
	v_exp_f32_e32 v65, v65
	v_mul_f32_e32 v58, 0xbfb8aa3b, v58
	v_mul_f32_e32 v59, 0xbfb8aa3b, v59
	v_exp_f32_e32 v58, v58
	v_exp_f32_e32 v59, v59
	v_add_f32_e32 v64, 1.0, v64
	v_add_f32_e32 v65, 1.0, v65
	v_rcp_f32_e32 v64, v64
	v_rcp_f32_e32 v65, v65
	v_add_f32_e32 v58, 1.0, v58
	v_add_f32_e32 v59, 1.0, v59
	v_rcp_f32_e32 v58, v58
	v_rcp_f32_e32 v59, v59
	v_mul_f32_e32 v62, v62, v152
	v_mul_f32_e32 v63, v63, v152
	v_mul_f32_e32 v62, 0xbfb8aa3b, v62
	v_mul_f32_e32 v63, 0xbfb8aa3b, v63
	v_exp_f32_e32 v62, v62
	v_exp_f32_e32 v63, v63
	v_mul_f32_e32 v54, v54, v152
	v_mul_f32_e32 v55, v55, v152
	v_add_f32_e32 v62, 1.0, v62
	v_add_f32_e32 v63, 1.0, v63
	v_rcp_f32_e32 v62, v62
	v_rcp_f32_e32 v63, v63
	v_mul_f32_e32 v54, 0xbfb8aa3b, v54
	v_mul_f32_e32 v55, 0xbfb8aa3b, v55
	v_mul_f32_e32 v56, v56, v152
	v_mul_f32_e32 v57, v57, v152
	v_exp_f32_e32 v54, v54
	v_exp_f32_e32 v55, v55
	v_mul_f32_e32 v56, 0xbfb8aa3b, v56
	v_mul_f32_e32 v57, 0xbfb8aa3b, v57
	v_mul_f32_e32 v50, v50, v152
	v_mul_f32_e32 v51, v51, v152
	v_exp_f32_e32 v56, v56
	v_exp_f32_e32 v57, v57
	v_mul_f32_e32 v50, 0xbfb8aa3b, v50
	v_mul_f32_e32 v51, 0xbfb8aa3b, v51
	v_exp_f32_e32 v50, v50
	v_exp_f32_e32 v51, v51
	v_add_f32_e32 v54, 1.0, v54
	v_add_f32_e32 v55, 1.0, v55
	v_rcp_f32_e32 v54, v54
	v_rcp_f32_e32 v55, v55
	v_add_f32_e32 v56, 1.0, v56
	v_add_f32_e32 v57, 1.0, v57
	v_rcp_f32_e32 v56, v56
	v_rcp_f32_e32 v57, v57
	v_add_f32_e32 v50, 1.0, v50
	v_add_f32_e32 v51, 1.0, v51
	v_rcp_f32_e32 v50, v50
	v_rcp_f32_e32 v51, v51
	v_add_f32_e32 v146, v154, v155
	v_add_f32_e32 v147, v156, v157
	v_lshlrev_b32_e32 v154, 16, v126
	v_and_b32_e32 v155, 0xffff0000, v126
	v_lshlrev_b32_e32 v156, 16, v122
	v_and_b32_e32 v157, 0xffff0000, v122
	v_lshlrev_b32_e32 v126, 16, v127
	v_and_b32_e32 v127, 0xffff0000, v127
	v_lshlrev_b32_e32 v122, 16, v123
	v_and_b32_e32 v123, 0xffff0000, v123
	v_pk_fma_f32 v[64:65], v[64:65], v[122:123], v[126:127]
	v_lshlrev_b32_e32 v122, 16, v128
	v_and_b32_e32 v123, 0xffff0000, v128
	v_lshlrev_b32_e32 v126, 16, v124
	v_and_b32_e32 v127, 0xffff0000, v124
	v_pk_fma_f32 v[122:123], v[58:59], v[126:127], v[122:123]
	v_mul_f32_e32 v58, v60, v152
	v_mul_f32_e32 v59, v61, v152
	v_mul_f32_e32 v58, 0xbfb8aa3b, v58
	v_mul_f32_e32 v59, 0xbfb8aa3b, v59
	v_exp_f32_e32 v58, v58
	v_exp_f32_e32 v59, v59
	v_pk_fma_f32 v[62:63], v[62:63], v[156:157], v[154:155]
	v_lshlrev_b32_e32 v60, 16, v129
	v_add_f32_e32 v58, 1.0, v58
	v_add_f32_e32 v59, 1.0, v59
	v_rcp_f32_e32 v58, v58
	v_rcp_f32_e32 v59, v59
	v_and_b32_e32 v61, 0xffff0000, v129
	v_lshlrev_b32_e32 v124, 16, v125
	v_and_b32_e32 v125, 0xffff0000, v125
	v_pk_fma_f32 v[124:125], v[58:59], v[124:125], v[60:61]
	v_cvt_pk_bf16_f32 v58, v62, v63
	v_lshl_add_u64 v[62:63], s[92:93], 0, v[144:145]
	v_cvt_pk_bf16_f32 v59, v64, v65
	v_cvt_pk_bf16_f32 v60, v122, v123
	v_cvt_pk_bf16_f32 v61, v124, v125
	v_lshl_add_u64 v[62:63], v[204:205], 1, v[62:63]
	global_store_dwordx4 v[62:63], v[58:61], off
	v_lshlrev_b32_e32 v64, 16, v58
	v_lshlrev_b32_e32 v65, 16, v59
	v_and_b32_e32 v58, 0xffff0000, v58
	v_and_b32_e32 v59, 0xffff0000, v59
	v_mul_f32_e32 v58, v58, v58
	v_mul_f32_e32 v59, v59, v59
	v_lshlrev_b32_e32 v122, 16, v60
	v_and_b32_e32 v60, 0xffff0000, v60
	v_fmac_f32_e32 v58, v64, v64
	v_fmac_f32_e32 v59, v65, v65
	v_add_f32_e32 v58, v58, v59
	v_mul_f32_e32 v59, v60, v60
	v_lshlrev_b32_e32 v123, 16, v61
	v_and_b32_e32 v61, 0xffff0000, v61
	v_fmac_f32_e32 v59, v122, v122
	v_add_f32_e32 v58, v59, v58
	v_mul_f32_e32 v59, v61, v61
	v_fmac_f32_e32 v59, v123, v123
	v_add_f32_e32 v64, v59, v58
	v_lshlrev_b32_e32 v58, 16, v118
	v_and_b32_e32 v59, 0xffff0000, v118
	v_lshlrev_b32_e32 v60, 16, v114
	v_and_b32_e32 v61, 0xffff0000, v114
	v_pk_fma_f32 v[54:55], v[54:55], v[60:61], v[58:59]
	v_lshlrev_b32_e32 v58, 16, v119
	v_and_b32_e32 v59, 0xffff0000, v119
	v_lshlrev_b32_e32 v60, 16, v115
	v_and_b32_e32 v61, 0xffff0000, v115
	v_pk_fma_f32 v[56:57], v[56:57], v[60:61], v[58:59]
	v_lshlrev_b32_e32 v58, 16, v120
	v_and_b32_e32 v59, 0xffff0000, v120
	v_lshlrev_b32_e32 v60, 16, v116
	v_and_b32_e32 v61, 0xffff0000, v116
	v_pk_fma_f32 v[58:59], v[50:51], v[60:61], v[58:59]
	v_mul_f32_e32 v50, v52, v152
	v_mul_f32_e32 v51, v53, v152
	v_mul_f32_e32 v50, 0xbfb8aa3b, v50
	v_mul_f32_e32 v51, 0xbfb8aa3b, v51
	v_exp_f32_e32 v50, v50
	v_exp_f32_e32 v51, v51
	v_lshlrev_b32_e32 v52, 16, v121
	v_and_b32_e32 v53, 0xffff0000, v121
	v_add_f32_e32 v50, 1.0, v50
	v_add_f32_e32 v51, 1.0, v51
	v_rcp_f32_e32 v50, v50
	v_rcp_f32_e32 v51, v51
	v_lshlrev_b32_e32 v60, 16, v117
	v_and_b32_e32 v61, 0xffff0000, v117
	v_add_f32_e32 v146, v146, v147
	v_pk_fma_f32 v[60:61], v[50:51], v[60:61], v[52:53]
	v_cvt_pk_bf16_f32 v50, v54, v55
	v_cvt_pk_bf16_f32 v51, v56, v57
	v_cvt_pk_bf16_f32 v52, v58, v59
	v_cvt_pk_bf16_f32 v53, v60, v61
	global_store_dwordx4 v[62:63], v[50:53], off offset:256
	v_lshlrev_b32_e32 v54, 16, v50
	v_lshlrev_b32_e32 v55, 16, v51
	v_and_b32_e32 v50, 0xffff0000, v50
	v_and_b32_e32 v51, 0xffff0000, v51
	v_mul_f32_e32 v50, v50, v50
	v_fmac_f32_e32 v50, v54, v54
	v_mul_f32_e32 v51, v51, v51
	v_lshlrev_b32_e32 v56, 16, v52
	v_and_b32_e32 v52, 0xffff0000, v52
	v_add_f32_e32 v50, v50, v64
	v_fmac_f32_e32 v51, v55, v55
	v_add_f32_e32 v50, v51, v50
	v_mul_f32_e32 v51, v52, v52
	v_lshlrev_b32_e32 v57, 16, v53
	v_and_b32_e32 v53, 0xffff0000, v53
	v_fmac_f32_e32 v51, v56, v56
	v_add_f32_e32 v50, v51, v50
	v_mul_f32_e32 v51, v53, v53
	v_fmac_f32_e32 v51, v57, v57
	v_add_f32_e32 v50, v51, v50
	ds_bpermute_b32 v147, v229, v146
	ds_bpermute_b32 v51, v229, v50
	s_waitcnt lgkmcnt(1)
	v_add_f32_e32 v146, v146, v147
	s_waitcnt lgkmcnt(0)
	v_add_f32_e32 v50, v50, v51
	ds_bpermute_b32 v147, v228, v146
	ds_bpermute_b32 v51, v228, v50
	s_and_saveexec_b64 s[10:11], vcc
	s_cbranch_execz .LBB0_958
	s_lshl_b32 s20, s82, 2
	v_lshl_add_u64 v[52:53], s[4:5], 0, v[142:143]
	s_ashr_i32 s21, s20, 31
	v_lshl_add_u64 v[52:53], s[20:21], 2, v[52:53]
	s_lshl_b32 s76, s19, 2
	v_lshl_add_u64 v[52:53], v[52:53], 0, s[76:77]
	s_waitcnt lgkmcnt(0)
	v_add_f32_e32 v50, v50, v51
	global_store_dword v[52:53], v50, off
.LBB0_958:
	s_or_b64 exec, exec, s[10:11]
	s_waitcnt vmcnt(3)
	v_add_f32_e32 v66, v66, v67
	v_add_f32_e32 v67, v68, v69
	v_add_f32_e32 v66, v66, v67
	ds_bpermute_b32 v67, v229, v66
	s_waitcnt lgkmcnt(0)
	v_add_f32_e32 v150, v66, v67
	v_lshlrev_b64 v[66:67], 10, v[134:135]
	v_lshl_add_u64 v[66:67], v[66:67], 0, v[204:205]
	v_lshlrev_b64 v[66:67], 1, v[66:67]
	v_lshl_add_u64 v[68:69], s[88:89], 0, v[66:67]
	v_lshl_add_u64 v[66:67], s[62:63], 0, v[66:67]
	global_load_dwordx4 v[94:97], v[68:69], off
	global_load_dwordx4 v[90:93], v[66:67], off
	global_load_dwordx4 v[86:89], v[68:69], off offset:256
	global_load_dwordx4 v[82:85], v[66:67], off offset:256
	v_lshl_add_u64 v[66:67], v[206:207], 0, v[136:137]
	global_load_dwordx4 v[66:69], v[66:67], off
	ds_bpermute_b32 v151, v228, v150
	s_waitcnt lgkmcnt(0)
	v_add_f32_e32 v50, v150, v151
	v_fmamk_f32 v50, v50, 0x3a800000, v240
	v_rsq_f32_e32 v54, v50
	v_lshlrev_b32_e32 v52, 16, v106
	v_and_b32_e32 v53, 0xffff0000, v106
	v_mul_f32_e32 v46, v46, v54
	v_mul_f32_e32 v47, v47, v54
	v_mul_f32_e32 v46, 0xbfb8aa3b, v46
	v_mul_f32_e32 v47, 0xbfb8aa3b, v47
	v_mul_f32_e32 v48, v48, v54
	v_mul_f32_e32 v49, v49, v54
	v_exp_f32_e32 v50, v46
	v_exp_f32_e32 v47, v47
	v_mul_f32_e32 v48, 0xbfb8aa3b, v48
	v_mul_f32_e32 v49, 0xbfb8aa3b, v49
	v_mul_f32_e32 v42, v42, v54
	v_mul_f32_e32 v43, v43, v54
	v_exp_f32_e32 v48, v48
	v_exp_f32_e32 v49, v49
	v_mul_f32_e32 v42, 0xbfb8aa3b, v42
	v_mul_f32_e32 v43, 0xbfb8aa3b, v43
	v_exp_f32_e32 v42, v42
	v_exp_f32_e32 v43, v43
	v_mul_f32_e32 v44, v44, v54
	v_add_f32_e32 v50, 1.0, v50
	v_add_f32_e32 v47, 1.0, v47
	v_mul_f32_e32 v44, 0xbfb8aa3b, v44
	v_rcp_f32_e32 v50, v50
	s_waitcnt lgkmcnt(0)
	v_rcp_f32_e32 v51, v47
	v_add_f32_e32 v48, 1.0, v48
	v_add_f32_e32 v49, 1.0, v49
	v_exp_f32_e32 v55, v44
	v_mul_f32_e32 v44, v45, v54
	v_rcp_f32_e32 v48, v48
	v_rcp_f32_e32 v49, v49
	v_add_f32_e32 v42, 1.0, v42
	v_add_f32_e32 v43, 1.0, v43
	v_mul_f32_e32 v44, 0xbfb8aa3b, v44
	v_rcp_f32_e32 v42, v42
	v_rcp_f32_e32 v43, v43
	v_exp_f32_e32 v56, v44
	v_lshlrev_b32_e32 v46, 16, v110
	v_and_b32_e32 v47, 0xffff0000, v110
	v_pk_fma_f32 v[46:47], v[50:51], v[52:53], v[46:47]
	v_lshlrev_b32_e32 v50, 16, v111
	v_and_b32_e32 v51, 0xffff0000, v111
	v_lshlrev_b32_e32 v52, 16, v107
	v_and_b32_e32 v53, 0xffff0000, v107
	v_pk_fma_f32 v[48:49], v[48:49], v[52:53], v[50:51]
	v_lshlrev_b32_e32 v50, 16, v112
	v_and_b32_e32 v51, 0xffff0000, v112
	v_lshlrev_b32_e32 v52, 16, v108
	v_and_b32_e32 v53, 0xffff0000, v108
	v_pk_fma_f32 v[44:45], v[42:43], v[52:53], v[50:51]
	v_add_f32_e32 v42, 1.0, v55
	v_add_f32_e32 v43, 1.0, v56
	v_rcp_f32_e32 v42, v42
	v_rcp_f32_e32 v43, v43
	v_lshlrev_b32_e32 v50, 16, v113
	v_and_b32_e32 v51, 0xffff0000, v113
	v_lshlrev_b32_e32 v52, 16, v109
	v_and_b32_e32 v53, 0xffff0000, v109
	v_pk_fma_f32 v[50:51], v[42:43], v[52:53], v[50:51]
	v_cvt_pk_bf16_f32 v42, v46, v47
	v_mul_f32_e32 v38, v38, v54
	v_mul_f32_e32 v39, v39, v54
	v_cvt_pk_bf16_f32 v43, v48, v49
	v_and_b32_e32 v47, 0xffff0000, v42
	v_mul_f32_e32 v38, 0xbfb8aa3b, v38
	v_mul_f32_e32 v39, 0xbfb8aa3b, v39
	v_mul_f32_e32 v40, v40, v54
	v_mul_f32_e32 v41, v41, v54
	v_lshlrev_b32_e32 v46, 16, v42
	v_and_b32_e32 v49, 0xffff0000, v43
	v_mul_f32_e32 v47, v47, v47
	v_exp_f32_e32 v38, v38
	v_exp_f32_e32 v39, v39
	v_mul_f32_e32 v40, 0xbfb8aa3b, v40
	v_mul_f32_e32 v41, 0xbfb8aa3b, v41
	v_cvt_pk_bf16_f32 v44, v44, v45
	v_lshlrev_b32_e32 v48, 16, v43
	v_fmac_f32_e32 v47, v46, v46
	v_mul_f32_e32 v46, v49, v49
	v_exp_f32_e32 v40, v40
	v_exp_f32_e32 v41, v41
	v_cvt_pk_bf16_f32 v45, v50, v51
	v_and_b32_e32 v51, 0xffff0000, v44
	v_fmac_f32_e32 v46, v48, v48
	v_mul_f32_e32 v34, v34, v54
	v_lshlrev_b32_e32 v50, 16, v44
	v_add_f32_e32 v46, v47, v46
	v_mul_f32_e32 v47, v51, v51
	v_mul_f32_e32 v34, 0xbfb8aa3b, v34
	v_and_b32_e32 v53, 0xffff0000, v45
	v_fmac_f32_e32 v47, v50, v50
	v_add_f32_e32 v38, 1.0, v38
	v_add_f32_e32 v39, 1.0, v39
	v_exp_f32_e32 v51, v34
	v_mul_f32_e32 v34, v35, v54
	v_lshlrev_b32_e32 v52, 16, v45
	v_add_f32_e32 v46, v47, v46
	v_mul_f32_e32 v47, v53, v53
	v_rcp_f32_e32 v38, v38
	v_rcp_f32_e32 v39, v39
	v_add_f32_e32 v40, 1.0, v40
	v_add_f32_e32 v41, 1.0, v41
	v_mul_f32_e32 v34, 0xbfb8aa3b, v34
	v_mul_f32_e32 v36, v36, v54
	v_mul_f32_e32 v37, v37, v54
	v_fmac_f32_e32 v47, v52, v52
	v_rcp_f32_e32 v40, v40
	v_rcp_f32_e32 v41, v41
	v_exp_f32_e32 v52, v34
	v_mul_f32_e32 v36, 0xbfb8aa3b, v36
	v_mul_f32_e32 v37, 0xbfb8aa3b, v37
	v_exp_f32_e32 v36, v36
	v_exp_f32_e32 v37, v37
	v_add_f32_e32 v50, v47, v46
	v_lshlrev_b32_e32 v46, 16, v102
	v_and_b32_e32 v47, 0xffff0000, v102
	v_lshlrev_b32_e32 v48, 16, v98
	v_and_b32_e32 v49, 0xffff0000, v98
	v_pk_fma_f32 v[38:39], v[38:39], v[48:49], v[46:47]
	v_lshlrev_b32_e32 v46, 16, v103
	v_and_b32_e32 v47, 0xffff0000, v103
	v_lshlrev_b32_e32 v48, 16, v99
	v_and_b32_e32 v49, 0xffff0000, v99
	v_pk_fma_f32 v[34:35], v[40:41], v[48:49], v[46:47]
	v_add_f32_e32 v40, 1.0, v51
	v_add_f32_e32 v41, 1.0, v52
	v_rcp_f32_e32 v40, v40
	v_rcp_f32_e32 v41, v41
	v_add_f32_e32 v36, 1.0, v36
	v_add_f32_e32 v37, 1.0, v37
	v_rcp_f32_e32 v36, v36
	v_rcp_f32_e32 v37, v37
	v_lshlrev_b32_e32 v46, 16, v104
	v_and_b32_e32 v47, 0xffff0000, v104
	v_lshlrev_b32_e32 v48, 16, v100
	v_and_b32_e32 v49, 0xffff0000, v100
	v_pk_fma_f32 v[40:41], v[40:41], v[48:49], v[46:47]
	v_lshlrev_b32_e32 v46, 16, v105
	v_and_b32_e32 v47, 0xffff0000, v105
	v_lshlrev_b32_e32 v48, 16, v101
	v_and_b32_e32 v49, 0xffff0000, v101
	v_pk_fma_f32 v[46:47], v[36:37], v[48:49], v[46:47]
	v_cvt_pk_bf16_f32 v36, v38, v39
	v_cvt_pk_bf16_f32 v37, v34, v35
	v_and_b32_e32 v35, 0xffff0000, v36
	v_lshlrev_b32_e32 v34, 16, v36
	v_mul_f32_e32 v35, v35, v35
	v_cvt_pk_bf16_f32 v38, v40, v41
	v_and_b32_e32 v41, 0xffff0000, v37
	v_fmac_f32_e32 v35, v34, v34
	v_lshlrev_b32_e32 v40, 16, v37
	v_add_f32_e32 v34, v35, v50
	v_mul_f32_e32 v35, v41, v41
	v_cvt_pk_bf16_f32 v39, v46, v47
	v_and_b32_e32 v47, 0xffff0000, v38
	v_fmac_f32_e32 v35, v40, v40
	v_lshlrev_b32_e32 v46, 16, v38
	v_add_f32_e32 v34, v35, v34
	v_mul_f32_e32 v35, v47, v47
	v_and_b32_e32 v49, 0xffff0000, v39
	v_fmac_f32_e32 v35, v46, v46
	v_lshlrev_b32_e32 v48, 16, v39
	v_add_f32_e32 v34, v35, v34
	v_mul_f32_e32 v35, v49, v49
	v_fmac_f32_e32 v35, v48, v48
	v_add_f32_e32 v34, v35, v34
	ds_bpermute_b32 v35, v229, v34
	v_lshlrev_b64 v[40:41], 11, v[140:141]
	v_lshl_add_u64 v[40:41], s[92:93], 0, v[40:41]
	v_lshl_add_u64 v[40:41], v[204:205], 1, v[40:41]
	global_store_dwordx4 v[40:41], v[42:45], off
	global_store_dwordx4 v[40:41], v[36:39], off offset:256
	s_waitcnt lgkmcnt(0)
	v_add_f32_e32 v34, v34, v35
	ds_bpermute_b32 v35, v228, v34
	s_and_saveexec_b64 s[10:11], vcc
	s_cbranch_execz .LBB0_960
	s_lshl_b32 s20, s82, 2
	v_lshl_add_u64 v[36:37], s[4:5], 0, v[138:139]
	s_ashr_i32 s21, s20, 31
	v_lshl_add_u64 v[36:37], s[20:21], 2, v[36:37]
	s_lshl_b32 s76, s19, 2
	v_lshl_add_u64 v[36:37], v[36:37], 0, s[76:77]
	s_waitcnt lgkmcnt(0)
	v_add_f32_e32 v34, v34, v35
	global_store_dword v[36:37], v34, off
.LBB0_960:
	s_or_b64 exec, exec, s[10:11]
	s_waitcnt vmcnt(3)
	v_add_f32_e32 v66, v66, v67
	v_add_f32_e32 v67, v68, v69
	v_add_f32_e32 v66, v66, v67
	ds_bpermute_b32 v67, v229, v66
	s_waitcnt lgkmcnt(0)
	v_add_f32_e32 v148, v66, v67
	v_lshlrev_b64 v[66:67], 10, v[130:131]
	v_lshl_add_u64 v[66:67], v[66:67], 0, v[204:205]
	v_lshlrev_b64 v[66:67], 1, v[66:67]
	v_lshl_add_u64 v[68:69], s[88:89], 0, v[66:67]
	v_lshl_add_u64 v[66:67], s[62:63], 0, v[66:67]
	global_load_dwordx4 v[78:81], v[68:69], off
	global_load_dwordx4 v[74:77], v[66:67], off
	global_load_dwordx4 v[70:73], v[68:69], off offset:256
	s_nop 0
	global_load_dwordx4 v[66:69], v[66:67], off offset:256
	ds_bpermute_b32 v149, v228, v148
	s_waitcnt lgkmcnt(0)
	v_add_f32_e32 v34, v148, v149
	v_fmamk_f32 v34, v34, 0x3a800000, v240
	v_rsq_f32_e32 v38, v34
	v_lshlrev_b32_e32 v36, 16, v90
	v_and_b32_e32 v37, 0xffff0000, v90
	v_mul_f32_e32 v30, v30, v38
	v_mul_f32_e32 v31, v31, v38
	v_mul_f32_e32 v30, 0xbfb8aa3b, v30
	v_mul_f32_e32 v31, 0xbfb8aa3b, v31
	v_mul_f32_e32 v32, v32, v38
	v_mul_f32_e32 v33, v33, v38
	v_exp_f32_e32 v34, v30
	v_exp_f32_e32 v31, v31
	v_mul_f32_e32 v32, 0xbfb8aa3b, v32
	v_mul_f32_e32 v33, 0xbfb8aa3b, v33
	v_mul_f32_e32 v26, v26, v38
	v_mul_f32_e32 v27, v27, v38
	v_exp_f32_e32 v32, v32
	v_exp_f32_e32 v33, v33
	v_mul_f32_e32 v26, 0xbfb8aa3b, v26
	v_mul_f32_e32 v27, 0xbfb8aa3b, v27
	v_exp_f32_e32 v26, v26
	v_exp_f32_e32 v27, v27
	v_mul_f32_e32 v28, v28, v38
	v_add_f32_e32 v34, 1.0, v34
	v_add_f32_e32 v31, 1.0, v31
	v_mul_f32_e32 v28, 0xbfb8aa3b, v28
	v_rcp_f32_e32 v34, v34
	s_waitcnt lgkmcnt(0)
	v_rcp_f32_e32 v35, v31
	v_add_f32_e32 v32, 1.0, v32
	v_add_f32_e32 v33, 1.0, v33
	v_exp_f32_e32 v39, v28
	v_mul_f32_e32 v28, v29, v38
	v_rcp_f32_e32 v32, v32
	v_rcp_f32_e32 v33, v33
	v_add_f32_e32 v26, 1.0, v26
	v_add_f32_e32 v27, 1.0, v27
	v_mul_f32_e32 v28, 0xbfb8aa3b, v28
	v_rcp_f32_e32 v26, v26
	v_rcp_f32_e32 v27, v27
	v_exp_f32_e32 v40, v28
	v_lshlrev_b32_e32 v30, 16, v94
	v_and_b32_e32 v31, 0xffff0000, v94
	v_pk_fma_f32 v[30:31], v[34:35], v[36:37], v[30:31]
	v_lshlrev_b32_e32 v34, 16, v95
	v_and_b32_e32 v35, 0xffff0000, v95
	v_lshlrev_b32_e32 v36, 16, v91
	v_and_b32_e32 v37, 0xffff0000, v91
	v_pk_fma_f32 v[32:33], v[32:33], v[36:37], v[34:35]
	v_lshlrev_b32_e32 v34, 16, v96
	v_and_b32_e32 v35, 0xffff0000, v96
	v_lshlrev_b32_e32 v36, 16, v92
	v_and_b32_e32 v37, 0xffff0000, v92
	v_pk_fma_f32 v[28:29], v[26:27], v[36:37], v[34:35]
	v_add_f32_e32 v26, 1.0, v39
	v_add_f32_e32 v27, 1.0, v40
	v_rcp_f32_e32 v26, v26
	v_rcp_f32_e32 v27, v27
	v_lshlrev_b32_e32 v34, 16, v97
	v_and_b32_e32 v35, 0xffff0000, v97
	v_lshlrev_b32_e32 v36, 16, v93
	v_and_b32_e32 v37, 0xffff0000, v93
	v_pk_fma_f32 v[34:35], v[26:27], v[36:37], v[34:35]
	v_cvt_pk_bf16_f32 v26, v30, v31
	v_mul_f32_e32 v22, v22, v38
	v_mul_f32_e32 v23, v23, v38
	v_cvt_pk_bf16_f32 v27, v32, v33
	v_and_b32_e32 v31, 0xffff0000, v26
	v_mul_f32_e32 v22, 0xbfb8aa3b, v22
	v_mul_f32_e32 v23, 0xbfb8aa3b, v23
	v_mul_f32_e32 v24, v24, v38
	v_mul_f32_e32 v25, v25, v38
	v_lshlrev_b32_e32 v30, 16, v26
	v_and_b32_e32 v33, 0xffff0000, v27
	v_mul_f32_e32 v31, v31, v31
	v_exp_f32_e32 v22, v22
	v_exp_f32_e32 v23, v23
	v_mul_f32_e32 v24, 0xbfb8aa3b, v24
	v_mul_f32_e32 v25, 0xbfb8aa3b, v25
	v_cvt_pk_bf16_f32 v28, v28, v29
	v_lshlrev_b32_e32 v32, 16, v27
	v_fmac_f32_e32 v31, v30, v30
	v_mul_f32_e32 v30, v33, v33
	v_exp_f32_e32 v24, v24
	v_exp_f32_e32 v25, v25
	v_cvt_pk_bf16_f32 v29, v34, v35
	v_and_b32_e32 v35, 0xffff0000, v28
	v_fmac_f32_e32 v30, v32, v32
	v_mul_f32_e32 v18, v18, v38
	v_lshlrev_b32_e32 v34, 16, v28
	v_add_f32_e32 v30, v31, v30
	v_mul_f32_e32 v31, v35, v35
	v_mul_f32_e32 v18, 0xbfb8aa3b, v18
	v_and_b32_e32 v37, 0xffff0000, v29
	v_fmac_f32_e32 v31, v34, v34
	v_add_f32_e32 v22, 1.0, v22
	v_add_f32_e32 v23, 1.0, v23
	v_exp_f32_e32 v35, v18
	v_mul_f32_e32 v18, v19, v38
	v_lshlrev_b32_e32 v36, 16, v29
	v_add_f32_e32 v30, v31, v30
	v_mul_f32_e32 v31, v37, v37
	v_rcp_f32_e32 v22, v22
	v_rcp_f32_e32 v23, v23
	v_add_f32_e32 v24, 1.0, v24
	v_add_f32_e32 v25, 1.0, v25
	v_mul_f32_e32 v18, 0xbfb8aa3b, v18
	v_mul_f32_e32 v20, v20, v38
	v_mul_f32_e32 v21, v21, v38
	v_fmac_f32_e32 v31, v36, v36
	v_rcp_f32_e32 v24, v24
	v_rcp_f32_e32 v25, v25
	v_exp_f32_e32 v36, v18
	v_mul_f32_e32 v20, 0xbfb8aa3b, v20
	v_mul_f32_e32 v21, 0xbfb8aa3b, v21
	v_exp_f32_e32 v20, v20
	v_exp_f32_e32 v21, v21
	v_add_f32_e32 v34, v31, v30
	v_lshlrev_b32_e32 v30, 16, v86
	v_and_b32_e32 v31, 0xffff0000, v86
	v_lshlrev_b32_e32 v32, 16, v82
	v_and_b32_e32 v33, 0xffff0000, v82
	v_pk_fma_f32 v[22:23], v[22:23], v[32:33], v[30:31]
	v_lshlrev_b32_e32 v30, 16, v87
	v_and_b32_e32 v31, 0xffff0000, v87
	v_lshlrev_b32_e32 v32, 16, v83
	v_and_b32_e32 v33, 0xffff0000, v83
	v_pk_fma_f32 v[18:19], v[24:25], v[32:33], v[30:31]
	v_add_f32_e32 v24, 1.0, v35
	v_add_f32_e32 v25, 1.0, v36
	v_rcp_f32_e32 v24, v24
	v_rcp_f32_e32 v25, v25
	v_add_f32_e32 v20, 1.0, v20
	v_add_f32_e32 v21, 1.0, v21
	v_rcp_f32_e32 v20, v20
	v_rcp_f32_e32 v21, v21
	v_lshlrev_b32_e32 v30, 16, v88
	v_and_b32_e32 v31, 0xffff0000, v88
	v_lshlrev_b32_e32 v32, 16, v84
	v_and_b32_e32 v33, 0xffff0000, v84
	v_pk_fma_f32 v[24:25], v[24:25], v[32:33], v[30:31]
	v_lshlrev_b32_e32 v30, 16, v89
	v_and_b32_e32 v31, 0xffff0000, v89
	v_lshlrev_b32_e32 v32, 16, v85
	v_and_b32_e32 v33, 0xffff0000, v85
	v_pk_fma_f32 v[30:31], v[20:21], v[32:33], v[30:31]
	v_cvt_pk_bf16_f32 v20, v22, v23
	v_cvt_pk_bf16_f32 v21, v18, v19
	v_and_b32_e32 v19, 0xffff0000, v20
	v_lshlrev_b32_e32 v18, 16, v20
	v_mul_f32_e32 v19, v19, v19
	v_cvt_pk_bf16_f32 v22, v24, v25
	v_and_b32_e32 v25, 0xffff0000, v21
	v_fmac_f32_e32 v19, v18, v18
	v_lshlrev_b32_e32 v24, 16, v21
	v_add_f32_e32 v18, v19, v34
	v_mul_f32_e32 v19, v25, v25
	v_cvt_pk_bf16_f32 v23, v30, v31
	v_and_b32_e32 v31, 0xffff0000, v22
	v_fmac_f32_e32 v19, v24, v24
	v_lshlrev_b32_e32 v30, 16, v22
	v_add_f32_e32 v18, v19, v18
	v_mul_f32_e32 v19, v31, v31
	v_and_b32_e32 v33, 0xffff0000, v23
	v_fmac_f32_e32 v19, v30, v30
	v_lshlrev_b32_e32 v32, 16, v23
	v_add_f32_e32 v18, v19, v18
	v_mul_f32_e32 v19, v33, v33
	v_fmac_f32_e32 v19, v32, v32
	v_add_f32_e32 v18, v19, v18
	ds_bpermute_b32 v19, v229, v18
	v_lshlrev_b64 v[24:25], 11, v[134:135]
	v_lshl_add_u64 v[24:25], s[92:93], 0, v[24:25]
	v_lshl_add_u64 v[24:25], v[204:205], 1, v[24:25]
	global_store_dwordx4 v[24:25], v[26:29], off
	global_store_dwordx4 v[24:25], v[20:23], off offset:256
	s_waitcnt lgkmcnt(0)
	v_add_f32_e32 v18, v18, v19
	ds_bpermute_b32 v19, v228, v18
	s_and_saveexec_b64 s[10:11], vcc
	s_cbranch_execz .LBB0_962
	s_lshl_b32 s20, s82, 2
	v_lshl_add_u64 v[20:21], s[4:5], 0, v[136:137]
	s_ashr_i32 s21, s20, 31
	v_lshl_add_u64 v[20:21], s[20:21], 2, v[20:21]
	s_lshl_b32 s76, s19, 2
	v_lshl_add_u64 v[20:21], v[20:21], 0, s[76:77]
	s_waitcnt lgkmcnt(0)
	v_add_f32_e32 v18, v18, v19
	global_store_dword v[20:21], v18, off
.LBB0_962:
	s_or_b64 exec, exec, s[10:11]
	s_waitcnt vmcnt(3)
	v_add_f32_e32 v18, v146, v147
	v_fmamk_f32 v18, v18, 0x3a800000, v240
	v_rsq_f32_e32 v22, v18
	v_lshlrev_b32_e32 v20, 16, v74
	v_and_b32_e32 v21, 0xffff0000, v74
	v_mul_f32_e32 v14, v14, v22
	v_mul_f32_e32 v15, v15, v22
	v_mul_f32_e32 v14, 0xbfb8aa3b, v14
	v_mul_f32_e32 v15, 0xbfb8aa3b, v15
	v_mul_f32_e32 v16, v16, v22
	v_mul_f32_e32 v17, v17, v22
	v_exp_f32_e32 v18, v14
	v_exp_f32_e32 v15, v15
	v_mul_f32_e32 v16, 0xbfb8aa3b, v16
	v_mul_f32_e32 v17, 0xbfb8aa3b, v17
	v_mul_f32_e32 v10, v10, v22
	v_mul_f32_e32 v11, v11, v22
	v_exp_f32_e32 v16, v16
	v_exp_f32_e32 v17, v17
	v_mul_f32_e32 v10, 0xbfb8aa3b, v10
	v_mul_f32_e32 v11, 0xbfb8aa3b, v11
	v_exp_f32_e32 v10, v10
	v_exp_f32_e32 v11, v11
	v_mul_f32_e32 v12, v12, v22
	v_add_f32_e32 v18, 1.0, v18
	v_add_f32_e32 v15, 1.0, v15
	v_mul_f32_e32 v12, 0xbfb8aa3b, v12
	v_rcp_f32_e32 v18, v18
	s_waitcnt lgkmcnt(0)
	v_rcp_f32_e32 v19, v15
	v_add_f32_e32 v16, 1.0, v16
	v_add_f32_e32 v17, 1.0, v17
	v_exp_f32_e32 v23, v12
	v_mul_f32_e32 v12, v13, v22
	v_rcp_f32_e32 v16, v16
	v_rcp_f32_e32 v17, v17
	v_add_f32_e32 v10, 1.0, v10
	v_add_f32_e32 v11, 1.0, v11
	v_mul_f32_e32 v12, 0xbfb8aa3b, v12
	v_rcp_f32_e32 v10, v10
	v_rcp_f32_e32 v11, v11
	v_exp_f32_e32 v24, v12
	v_lshlrev_b32_e32 v14, 16, v78
	v_and_b32_e32 v15, 0xffff0000, v78
	v_pk_fma_f32 v[14:15], v[18:19], v[20:21], v[14:15]
	v_lshlrev_b32_e32 v18, 16, v79
	v_and_b32_e32 v19, 0xffff0000, v79
	v_lshlrev_b32_e32 v20, 16, v75
	v_and_b32_e32 v21, 0xffff0000, v75
	v_pk_fma_f32 v[16:17], v[16:17], v[20:21], v[18:19]
	v_lshlrev_b32_e32 v18, 16, v80
	v_and_b32_e32 v19, 0xffff0000, v80
	v_lshlrev_b32_e32 v20, 16, v76
	v_and_b32_e32 v21, 0xffff0000, v76
	v_pk_fma_f32 v[12:13], v[10:11], v[20:21], v[18:19]
	v_add_f32_e32 v10, 1.0, v23
	v_add_f32_e32 v11, 1.0, v24
	v_rcp_f32_e32 v10, v10
	v_rcp_f32_e32 v11, v11
	v_lshlrev_b32_e32 v18, 16, v81
	v_and_b32_e32 v19, 0xffff0000, v81
	v_lshlrev_b32_e32 v20, 16, v77
	v_and_b32_e32 v21, 0xffff0000, v77
	v_pk_fma_f32 v[18:19], v[10:11], v[20:21], v[18:19]
	v_cvt_pk_bf16_f32 v10, v14, v15
	v_mul_f32_e32 v6, v6, v22
	v_mul_f32_e32 v7, v7, v22
	v_cvt_pk_bf16_f32 v11, v16, v17
	v_and_b32_e32 v15, 0xffff0000, v10
	v_mul_f32_e32 v6, 0xbfb8aa3b, v6
	v_mul_f32_e32 v7, 0xbfb8aa3b, v7
	v_mul_f32_e32 v8, v8, v22
	v_mul_f32_e32 v9, v9, v22
	v_lshlrev_b32_e32 v14, 16, v10
	v_and_b32_e32 v17, 0xffff0000, v11
	v_mul_f32_e32 v15, v15, v15
	v_exp_f32_e32 v6, v6
	v_exp_f32_e32 v7, v7
	v_mul_f32_e32 v8, 0xbfb8aa3b, v8
	v_mul_f32_e32 v9, 0xbfb8aa3b, v9
	v_cvt_pk_bf16_f32 v12, v12, v13
	v_lshlrev_b32_e32 v16, 16, v11
	v_fmac_f32_e32 v15, v14, v14
	v_mul_f32_e32 v14, v17, v17
	v_exp_f32_e32 v8, v8
	v_exp_f32_e32 v9, v9
	v_cvt_pk_bf16_f32 v13, v18, v19
	v_and_b32_e32 v19, 0xffff0000, v12
	v_fmac_f32_e32 v14, v16, v16
	v_mul_f32_e32 v2, v2, v22
	v_lshlrev_b32_e32 v18, 16, v12
	v_add_f32_e32 v14, v15, v14
	v_mul_f32_e32 v15, v19, v19
	v_mul_f32_e32 v2, 0xbfb8aa3b, v2
	v_and_b32_e32 v21, 0xffff0000, v13
	v_fmac_f32_e32 v15, v18, v18
	v_add_f32_e32 v6, 1.0, v6
	v_add_f32_e32 v7, 1.0, v7
	v_exp_f32_e32 v19, v2
	v_mul_f32_e32 v2, v3, v22
	v_lshlrev_b32_e32 v20, 16, v13
	v_add_f32_e32 v14, v15, v14
	v_mul_f32_e32 v15, v21, v21
	v_rcp_f32_e32 v6, v6
	v_rcp_f32_e32 v7, v7
	v_add_f32_e32 v8, 1.0, v8
	v_add_f32_e32 v9, 1.0, v9
	v_mul_f32_e32 v2, 0xbfb8aa3b, v2
	v_mul_f32_e32 v4, v4, v22
	v_mul_f32_e32 v5, v5, v22
	v_fmac_f32_e32 v15, v20, v20
	v_rcp_f32_e32 v8, v8
	v_rcp_f32_e32 v9, v9
	v_exp_f32_e32 v20, v2
	v_mul_f32_e32 v4, 0xbfb8aa3b, v4
	v_mul_f32_e32 v5, 0xbfb8aa3b, v5
	v_exp_f32_e32 v4, v4
	v_exp_f32_e32 v5, v5
	v_add_f32_e32 v18, v15, v14
	v_lshlrev_b32_e32 v14, 16, v70
	v_and_b32_e32 v15, 0xffff0000, v70
	v_lshlrev_b32_e32 v16, 16, v66
	v_and_b32_e32 v17, 0xffff0000, v66
	v_pk_fma_f32 v[6:7], v[6:7], v[16:17], v[14:15]
	v_lshlrev_b32_e32 v14, 16, v71
	v_and_b32_e32 v15, 0xffff0000, v71
	v_lshlrev_b32_e32 v16, 16, v67
	v_and_b32_e32 v17, 0xffff0000, v67
	v_pk_fma_f32 v[2:3], v[8:9], v[16:17], v[14:15]
	v_add_f32_e32 v8, 1.0, v19
	v_add_f32_e32 v9, 1.0, v20
	v_rcp_f32_e32 v8, v8
	v_rcp_f32_e32 v9, v9
	v_add_f32_e32 v4, 1.0, v4
	v_add_f32_e32 v5, 1.0, v5
	v_rcp_f32_e32 v4, v4
	v_rcp_f32_e32 v5, v5
	v_lshlrev_b32_e32 v14, 16, v72
	v_and_b32_e32 v15, 0xffff0000, v72
	v_lshlrev_b32_e32 v16, 16, v68
	v_and_b32_e32 v17, 0xffff0000, v68
	v_pk_fma_f32 v[8:9], v[8:9], v[16:17], v[14:15]
	v_lshlrev_b32_e32 v14, 16, v73
	v_and_b32_e32 v15, 0xffff0000, v73
	v_lshlrev_b32_e32 v16, 16, v69
	v_and_b32_e32 v17, 0xffff0000, v69
	v_pk_fma_f32 v[14:15], v[4:5], v[16:17], v[14:15]
	v_cvt_pk_bf16_f32 v4, v6, v7
	v_cvt_pk_bf16_f32 v5, v2, v3
	v_and_b32_e32 v3, 0xffff0000, v4
	v_lshlrev_b32_e32 v2, 16, v4
	v_mul_f32_e32 v3, v3, v3
	v_cvt_pk_bf16_f32 v6, v8, v9
	v_and_b32_e32 v9, 0xffff0000, v5
	v_fmac_f32_e32 v3, v2, v2
	v_lshlrev_b32_e32 v8, 16, v5
	v_add_f32_e32 v2, v3, v18
	v_mul_f32_e32 v3, v9, v9
	v_cvt_pk_bf16_f32 v7, v14, v15
	v_and_b32_e32 v15, 0xffff0000, v6
	v_fmac_f32_e32 v3, v8, v8
	v_lshlrev_b32_e32 v14, 16, v6
	v_add_f32_e32 v2, v3, v2
	v_mul_f32_e32 v3, v15, v15
	v_and_b32_e32 v17, 0xffff0000, v7
	v_fmac_f32_e32 v3, v14, v14
	v_lshlrev_b32_e32 v16, 16, v7
	v_add_f32_e32 v2, v3, v2
	v_mul_f32_e32 v3, v17, v17
	v_fmac_f32_e32 v3, v16, v16
	v_add_f32_e32 v2, v3, v2
	ds_bpermute_b32 v3, v229, v2
	v_lshlrev_b64 v[8:9], 11, v[130:131]
	v_lshl_add_u64 v[8:9], s[92:93], 0, v[8:9]
	v_lshl_add_u64 v[8:9], v[204:205], 1, v[8:9]
	global_store_dwordx4 v[8:9], v[10:13], off
	global_store_dwordx4 v[8:9], v[4:7], off offset:256
	s_waitcnt lgkmcnt(0)
	v_add_f32_e32 v2, v2, v3
	ds_bpermute_b32 v3, v228, v2
	s_and_saveexec_b64 s[10:11], vcc
	s_cbranch_execz .LBB0_964
	s_lshl_b32 s20, s82, 2
	v_lshl_add_u64 v[4:5], s[4:5], 0, v[132:133]
	s_ashr_i32 s21, s20, 31
	v_lshl_add_u64 v[4:5], s[20:21], 2, v[4:5]
	s_lshl_b32 s76, s19, 2
	v_lshl_add_u64 v[4:5], v[4:5], 0, s[76:77]
	s_waitcnt lgkmcnt(0)
	v_add_f32_e32 v2, v2, v3
	global_store_dword v[4:5], v2, off
